# scan second MFMA group (12 mfma / 18 fragment reads) deep-pipelined into free VGPRs, accumulate in place
# baseline (speedup 1.0000x reference)
.LBB0_474:
	v_ashrrev_i32_e32 v0, 6, v89
	v_lshrrev_b32_e32 v90, 4, v89
	v_lshlrev_b32_e32 v74, 8, v92
	v_lshl_add_u32 v93, v0, 12, 0
	v_bitop3_b32 v75, v90, v92, 3 bitop3:0x6c
	v_add_u32_e32 v91, v93, v74
	v_lshlrev_b32_e32 v75, 4, v75
	v_add_u32_e32 v76, v91, v75
	ds_read_b128 v[82:85], v76
	v_add_u32_e32 v118, 0, v74
	v_add_u32_e32 v144, v118, v75
	ds_read_b128 v[128:131], v144 offset:16384
	ds_read_b128 v[132:135], v144 offset:20480
	ds_read_b128 v[136:139], v144 offset:24576
	ds_read_b128 v[140:143], v144 offset:28672
	v_bfe_u32 v119, v89, 4, 2
	v_bitop3_b32 v77, v119, v92, 4 bitop3:0x36
	v_lshlrev_b32_e32 v77, 4, v77
	v_add_u32_e32 v80, v91, v77
	ds_read_b128 v[110:113], v80
	v_add_u32_e32 v146, v118, v77
	ds_read_b128 v[150:153], v146 offset:16384
	ds_read_b128 v[154:157], v146 offset:20480
	ds_read_b128 v[158:161], v146 offset:24576
	ds_read_b128 v[162:165], v146 offset:28672
	v_bitop3_b32 v78, v119, v92, 8 bitop3:0x36
	v_lshlrev_b32_e32 v78, 4, v78
	v_add_u32_e32 v81, v91, v78
	ds_read_b128 v[114:117], v81
	v_add_u32_e32 v147, v118, v78
	v_bitop3_b32 v79, v119, v92, 12 bitop3:0x36
	v_lshlrev_b32_e32 v79, 4, v79
	v_add_u32_e32 v120, v91, v79
	v_add_u32_e32 v167, v118, v79
	v_lshrrev_b32_e32 v89, 3, v89
	s_and_b32 s1, s29, 0x2000
	s_add_i32 s1, s1, 0
	s_mov_b64 s[16:17], -1
	s_waitcnt lgkmcnt(9)
	v_mfma_f32_16x16x32_bf16 v[94:97], v[82:85], v[128:131], 0
	ds_read_b128 v[128:131], v147 offset:16384
	s_waitcnt lgkmcnt(9)
	v_mfma_f32_16x16x32_bf16 v[102:105], v[82:85], v[132:135], 0
	ds_read_b128 v[132:135], v147 offset:20480
	s_waitcnt lgkmcnt(9)
	v_mfma_f32_16x16x32_bf16 v[98:101], v[82:85], v[136:139], 0
	ds_read_b128 v[136:139], v147 offset:24576
	s_waitcnt lgkmcnt(9)
	v_mfma_f32_16x16x32_bf16 v[106:109], v[82:85], v[140:143], 0
	ds_read_b128 v[140:143], v147 offset:28672
	ds_read_b128 v[82:85], v120
	s_waitcnt lgkmcnt(9)
	v_mfma_f32_16x16x32_bf16 v[94:97], v[110:113], v[150:153], v[94:97]
	ds_read_b128 v[150:153], v167 offset:16384
	s_waitcnt lgkmcnt(9)
	v_mfma_f32_16x16x32_bf16 v[102:105], v[110:113], v[154:157], v[102:105]
	ds_read_b128 v[154:157], v167 offset:20480
	s_waitcnt lgkmcnt(9)
	v_mfma_f32_16x16x32_bf16 v[98:101], v[110:113], v[158:161], v[98:101]
	ds_read_b128 v[158:161], v167 offset:24576
	s_waitcnt lgkmcnt(9)
	v_mfma_f32_16x16x32_bf16 v[106:109], v[110:113], v[162:165], v[106:109]
	ds_read_b128 v[162:165], v167 offset:28672
	s_waitcnt lgkmcnt(8)
	v_mfma_f32_16x16x32_bf16 v[94:97], v[114:117], v[128:131], v[94:97]
	s_waitcnt lgkmcnt(7)
	v_mfma_f32_16x16x32_bf16 v[102:105], v[114:117], v[132:135], v[102:105]
	s_waitcnt lgkmcnt(6)
	v_mfma_f32_16x16x32_bf16 v[98:101], v[114:117], v[136:139], v[98:101]
	s_waitcnt lgkmcnt(5)
	v_mfma_f32_16x16x32_bf16 v[106:109], v[114:117], v[140:143], v[106:109]
	s_waitcnt lgkmcnt(3)
	v_mfma_f32_16x16x32_bf16 v[94:97], v[82:85], v[150:153], v[94:97]
	s_waitcnt lgkmcnt(2)
	v_mfma_f32_16x16x32_bf16 v[102:105], v[82:85], v[154:157], v[102:105]
	s_waitcnt lgkmcnt(1)
	v_mfma_f32_16x16x32_bf16 v[98:101], v[82:85], v[158:161], v[98:101]
	s_waitcnt lgkmcnt(0)
	v_mfma_f32_16x16x32_bf16 v[106:109], v[82:85], v[162:165], v[106:109]
	v_add_u32_e32 v91, v118, v79
	v_lshlrev_b32_e32 v83, 2, v119
	v_lshl_or_b32 v82, v0, 4, v83
	v_lshrrev_b32_e32 v84, 3, v92
	v_lshrrev_b32_e32 v85, 1, v83
	v_xor_b32_e32 v85, v85, v84
	v_lshlrev_b32_e32 v85, 4, v85
	v_lshl_add_u32 v84, v82, 7, v85
	v_add_u32_e32 v84, v84, v87
	v_xor_b32_e32 v85, 16, v84
	v_add_u32_e32 v85, 0x100, v85
	v_sub_u32_e32 v112, v92, v82
	v_sub_u32_e32 v113, 0, v112
	v_cndmask_b32_e64 v112, v113, v112, s[4:5]
	v_mov_b32_e32 v113, -16
	v_cndmask_b32_e64 v113, v113, 16, s[4:5]
	v_mov_b32_e32 v114, -1
	v_cndmask_b32_e64 v114, v114, 1, s[4:5]
	v_add_u32_e32 v115, v114, v114
	v_add_u32_e32 v116, v115, v114
	v_cmp_ge_i32_e64 s[98:99], 0, v112
	v_cmp_le_i32_e64 s[100:101], v112, v114
	v_cmp_le_i32_e32 vcc, v112, v115
	v_cndmask_b32_e64 v94, 0, v94, s[98:99]
	v_cndmask_b32_e64 v95, 0, v95, s[100:101]
	v_cmp_le_i32_e64 s[98:99], v112, v116
	v_cndmask_b32_e32 v96, 0, v96, vcc
	v_cvt_pk_bf16_f32 v94, v94, v95
	v_cndmask_b32_e64 v97, 0, v97, s[98:99]
	v_cvt_pk_bf16_f32 v96, v96, v97
	ds_write_b16 v84, v94 offset:53248
	ds_write_b16_d16_hi v84, v94 offset:53376
	ds_write_b16 v85, v96 offset:53248
	ds_write_b16_d16_hi v85, v96 offset:53376
	v_add_u32_e32 v112, v112, v113
	v_xor_b32_e32 v91, 0x20, v84
	v_xor_b32_e32 v110, 0x20, v85
	v_cmp_ge_i32_e64 s[98:99], 0, v112
	v_cmp_le_i32_e64 s[100:101], v112, v114
	v_cmp_le_i32_e32 vcc, v112, v115
	v_cndmask_b32_e64 v102, 0, v102, s[98:99]
	v_cndmask_b32_e64 v103, 0, v103, s[100:101]
	v_cmp_le_i32_e64 s[98:99], v112, v116
	v_cndmask_b32_e32 v104, 0, v104, vcc
	v_cvt_pk_bf16_f32 v102, v102, v103
	v_cndmask_b32_e64 v105, 0, v105, s[98:99]
	v_cvt_pk_bf16_f32 v104, v104, v105
	ds_write_b16 v91, v102 offset:53248
	ds_write_b16_d16_hi v91, v102 offset:53376
	ds_write_b16 v110, v104 offset:53248
	ds_write_b16_d16_hi v110, v104 offset:53376
	v_add_u32_e32 v112, v112, v113
	v_xor_b32_e32 v91, 0x40, v84
	v_xor_b32_e32 v110, 0x40, v85
	v_cmp_ge_i32_e64 s[98:99], 0, v112
	v_cmp_le_i32_e64 s[100:101], v112, v114
	v_cmp_le_i32_e32 vcc, v112, v115
	v_cndmask_b32_e64 v98, 0, v98, s[98:99]
	v_cndmask_b32_e64 v99, 0, v99, s[100:101]
	v_cmp_le_i32_e64 s[98:99], v112, v116
	v_cndmask_b32_e32 v100, 0, v100, vcc
	v_cvt_pk_bf16_f32 v98, v98, v99
	v_cndmask_b32_e64 v101, 0, v101, s[98:99]
	v_cvt_pk_bf16_f32 v100, v100, v101
	ds_write_b16 v91, v98 offset:53248
	ds_write_b16_d16_hi v91, v98 offset:53376
	ds_write_b16 v110, v100 offset:53248
	ds_write_b16_d16_hi v110, v100 offset:53376
	v_add_u32_e32 v112, v112, v113
	v_xor_b32_e32 v91, 0x60, v84
	v_xor_b32_e32 v110, 0x60, v85
	v_cmp_ge_i32_e64 s[98:99], 0, v112
	v_cmp_le_i32_e64 s[100:101], v112, v114
	v_cmp_le_i32_e32 vcc, v112, v115
	v_cndmask_b32_e64 v106, 0, v106, s[98:99]
	v_cndmask_b32_e64 v107, 0, v107, s[100:101]
	v_cmp_le_i32_e64 s[98:99], v112, v116
	v_cndmask_b32_e32 v108, 0, v108, vcc
	v_cvt_pk_bf16_f32 v106, v106, v107
	v_cndmask_b32_e64 v109, 0, v109, s[98:99]
	v_cvt_pk_bf16_f32 v108, v108, v109
	ds_write_b16 v91, v106 offset:53248
	ds_write_b16_d16_hi v91, v106 offset:53376
	ds_write_b16 v110, v108 offset:53248
	ds_write_b16_d16_hi v110, v108 offset:53376
	v_lshlrev_b32_e32 v111, 7, v92
	v_bitop3_b32 v89, v90, v88, 3 bitop3:0x6c
	s_add_i32 s0, 0, 0x13000
	v_lshlrev_b32_e32 v84, 7, v0
	v_lshlrev_b32_e32 v85, 2, v92
	v_add3_u32 v84, s0, v84, v85
	ds_read2_b32 v[84:85], v84 offset1:16
	v_add_u32_e32 v112, 0, v111
	v_lshlrev_b32_e32 v113, 4, v89
	v_add_u32_e32 v114, v112, v113
	ds_read_b128 v[94:97], v114 offset:49152
	s_waitcnt lgkmcnt(1)
	v_pk_mul_f32 v[40:41], v[40:41], v[84:85] op_sel_hi:[1,0]
	v_pk_mul_f32 v[38:39], v[38:39], v[84:85] op_sel_hi:[1,0]
	v_pk_mul_f32 v[48:49], v[48:49], v[84:85] op_sel_hi:[1,0]
	v_pk_mul_f32 v[46:47], v[46:47], v[84:85] op_sel_hi:[1,0]
	v_bitop3_b32 v84, v119, v88, 4 bitop3:0x36
	v_add3_u32 v89, v93, v113, v111
	v_lshlrev_b32_e32 v84, 4, v84
	ds_read_b128 v[98:101], v89 offset:32768
	ds_read_b128 v[102:105], v114 offset:51200
	ds_read_b128 v[106:109], v89 offset:34816
	v_mov_b32_e32 v110, v85
	v_add_u32_e32 v85, v112, v84
	ds_read_b128 v[88:91], v85 offset:49152
	v_pk_mul_f32 v[44:45], v[44:45], v[110:111] op_sel_hi:[1,0]
	v_pk_mul_f32 v[42:43], v[42:43], v[110:111] op_sel_hi:[1,0]
	v_pk_mul_f32 v[52:53], v[52:53], v[110:111] op_sel_hi:[1,0]
	v_pk_mul_f32 v[50:51], v[50:51], v[110:111] op_sel_hi:[1,0]
	v_add3_u32 v93, v93, v84, v111
	s_waitcnt lgkmcnt(3)
	v_mfma_f32_16x16x32_bf16 v[38:41], v[94:97], v[98:101], v[38:41]
	s_add_i32 s0, s29, 0xffffe000
	s_and_b32 s0, s0, 0x2000
	s_andn2_b64 vcc, exec, s[8:9]
	s_waitcnt lgkmcnt(1)
	v_mfma_f32_16x16x32_bf16 v[42:45], v[94:97], v[106:109], v[42:45]
	v_mfma_f32_16x16x32_bf16 v[46:49], v[102:105], v[98:101], v[46:49]
	v_mfma_f32_16x16x32_bf16 v[50:53], v[102:105], v[106:109], v[50:53]
	ds_read_b128 v[94:97], v93 offset:32768
	ds_read_b128 v[98:101], v85 offset:51200
	ds_read_b128 v[102:105], v93 offset:34816
	s_waitcnt lgkmcnt(2)
	v_mfma_f32_16x16x32_bf16 v[38:41], v[88:91], v[94:97], v[38:41]
	s_waitcnt lgkmcnt(0)
	v_mfma_f32_16x16x32_bf16 v[42:45], v[88:91], v[102:105], v[42:45]
	v_lshl_or_b32 v88, v0, 5, v92
	v_lshrrev_b32_e32 v88, 3, v88
	v_or_b32_e32 v89, 1, v83
	v_mfma_f32_16x16x32_bf16 v[46:49], v[98:101], v[94:97], v[46:49]
	v_xor_b32_e32 v95, v88, v83
	v_lshlrev_b32_e32 v95, 4, v95
	v_lshlrev_b32_e32 v94, 10, v119
	v_add3_u32 v95, s1, v95, v87
	v_bitop3_b32 v97, v83, v88, 1 bitop3:0x36
	v_cvt_pk_bf16_f32 v93, v38, s0
	v_add_u32_e32 v96, v95, v94
	v_lshlrev_b32_e32 v97, 4, v97
	ds_write_b16 v96, v93 offset:61440
	v_lshlrev_b32_e32 v96, 8, v89
	v_add3_u32 v97, s1, v97, v87
	v_mfma_f32_16x16x32_bf16 v[50:53], v[98:101], v[102:105], v[50:53]
	v_cvt_pk_bf16_f32 v93, v39, s0
	v_add_u32_e32 v98, v97, v96
	ds_write_b16 v98, v93 offset:61440
	v_bitop3_b32 v98, v83, v88, 2 bitop3:0x36
	v_or_b32_e32 v90, 2, v83
	v_lshlrev_b32_e32 v98, 4, v98
	v_lshlrev_b32_e32 v90, 8, v90
	v_add3_u32 v98, s1, v98, v87
	v_bitop3_b32 v100, v83, v88, 3 bitop3:0x36
	v_or_b32_e32 v91, 3, v83
	v_cvt_pk_bf16_f32 v93, v40, s0
	v_add_u32_e32 v99, v98, v90
	v_lshlrev_b32_e32 v100, 4, v100
	ds_write_b16 v99, v93 offset:61440
	v_lshlrev_b32_e32 v99, 8, v91
	v_add3_u32 v100, s1, v100, v87
	v_cvt_pk_bf16_f32 v93, v41, s0
	v_add_u32_e32 v101, v100, v99
	ds_write_b16 v101, v93 offset:61440
	v_bitop3_b32 v101, v88, v83, 2 bitop3:0x36
	v_lshlrev_b32_e32 v101, 4, v101
	v_bitop3_b32 v89, v88, v89, 2 bitop3:0x36
	v_add3_u32 v101, s1, v101, v87
	v_lshlrev_b32_e32 v89, 4, v89
	v_bitop3_b32 v83, v88, v83, 2 bitop3:0x14
	v_cvt_pk_bf16_f32 v93, v42, s0
	v_add_u32_e32 v102, v101, v94
	v_add3_u32 v89, s1, v89, v87
	v_lshlrev_b32_e32 v83, 4, v83
	v_bitop3_b32 v88, v88, v91, 2 bitop3:0x36
	ds_write_b16 v102, v93 offset:61440
	v_cvt_pk_bf16_f32 v93, v43, s0
	v_add_u32_e32 v96, v89, v96
	v_add3_u32 v83, s1, v83, v87
	v_lshlrev_b32_e32 v88, 4, v88
	ds_write_b16 v96, v93 offset:61440
	v_cvt_pk_bf16_f32 v93, v44, s0
	v_add_u32_e32 v90, v83, v90
	v_add3_u32 v87, s1, v88, v87
	ds_write_b16 v90, v93 offset:61440
	v_cvt_pk_bf16_f32 v90, v45, s0
	v_add_u32_e32 v88, v87, v99
	ds_write_b16 v88, v90 offset:61440
	v_or_b32_e32 v90, 0x1000, v94
	v_cvt_pk_bf16_f32 v88, v46, s0
	v_add_u32_e32 v91, v95, v90
	ds_write_b16 v91, v88 offset:61440
	v_or_b32_e32 v91, 0x1100, v94
	v_cvt_pk_bf16_f32 v88, v47, s0
	v_add_u32_e32 v93, v97, v91
	ds_write_b16 v93, v88 offset:61440
	v_or_b32_e32 v93, 0x1200, v94
	v_cvt_pk_bf16_f32 v88, v48, s0
	v_add_u32_e32 v95, v98, v93
	v_or_b32_e32 v94, 0x1300, v94
	ds_write_b16 v95, v88 offset:61440
	v_cvt_pk_bf16_f32 v88, v49, s0
	v_add_u32_e32 v95, v100, v94
	ds_write_b16 v95, v88 offset:61440
	v_cvt_pk_bf16_f32 v88, v50, s0
	v_add_u32_e32 v90, v101, v90
	ds_write_b16 v90, v88 offset:61440
	v_cvt_pk_bf16_f32 v88, v51, s0
	v_add_u32_e32 v89, v89, v91
	ds_write_b16 v89, v88 offset:61440
	v_cvt_pk_bf16_f32 v88, v52, s0
	v_add_u32_e32 v83, v83, v93
	ds_write_b16 v83, v88 offset:61440
	v_cvt_pk_bf16_f32 v83, v53, s0
	v_add_u32_e32 v87, v87, v94
	ds_write_b16 v87, v83 offset:61440
	s_waitcnt lgkmcnt(0)
	s_barrier
	s_add_i32 s0, s0, 0
	v_add_u32_e32 v83, s0, v74
	ds_read_b128 v[128:131], v76
	v_add_u32_e32 v144, v83, v75
	ds_read_b128 v[132:135], v144 offset:61440
	v_add_u32_e32 v144, 0xf000, v144
	ds_read_b128 v[136:139], v144 offset:4096
	ds_read_b128 v[140:143], v80
	v_add_u32_e32 v146, v83, v77
	ds_read_b128 v[150:153], v146 offset:61440
	v_add_u32_e32 v146, 0xf000, v146
	ds_read_b128 v[154:157], v146 offset:4096
	ds_read_b128 v[158:161], v81
	v_add_u32_e32 v147, v83, v78
	ds_read_b128 v[162:165], v147 offset:61440
	v_add_u32_e32 v147, 0xf000, v147
	ds_read_b128 v[102:105], v147 offset:4096
	ds_read_b128 v[106:109], v120
	v_add_u32_e32 v167, v83, v79
	ds_read_b128 v[88:91], v167 offset:61440
	v_add_u32_e32 v167, 0xf000, v167
	v_lshl_add_u32 v0, v0, 11, v112
	v_add_u32_e32 v168, v0, v113
	v_add_u32_e32 v169, v0, v84
	v_cndmask_b32_e64 v0, 0, 1, s[8:9]
	v_add_u32_e32 v84, s30, v82
	s_waitcnt lgkmcnt(9)
	v_mfma_f32_16x16x32_bf16 v[78:81], v[128:131], v[132:135], 0
	s_waitcnt lgkmcnt(8)
	v_mfma_f32_16x16x32_bf16 v[74:77], v[128:131], v[136:139], 0
	ds_read_b128 v[132:135], v167 offset:4096
	ds_read_b128 v[136:139], v168 offset:53248
	ds_read_b128 v[128:131], v114 offset:49152
	s_waitcnt lgkmcnt(9)
	v_mfma_f32_16x16x32_bf16 v[78:81], v[140:143], v[150:153], v[78:81]
	s_waitcnt lgkmcnt(8)
	v_mfma_f32_16x16x32_bf16 v[74:77], v[140:143], v[154:157], v[74:77]
	ds_read_b128 v[140:143], v114 offset:51200
	ds_read_b128 v[150:153], v169 offset:53248
	ds_read_b128 v[154:157], v85 offset:49152
	s_waitcnt lgkmcnt(9)
	v_mfma_f32_16x16x32_bf16 v[78:81], v[158:161], v[162:165], v[78:81]
	s_waitcnt lgkmcnt(8)
	v_mfma_f32_16x16x32_bf16 v[74:77], v[158:161], v[102:105], v[74:77]
	ds_read_b128 v[158:161], v85 offset:51200
	v_cmp_ne_u32_e64 s[6:7], 1, v0
	s_waitcnt lgkmcnt(7)
	v_mfma_f32_16x16x32_bf16 v[78:81], v[106:109], v[88:91], v[78:81]
	s_waitcnt lgkmcnt(6)
	v_mfma_f32_16x16x32_bf16 v[74:77], v[106:109], v[132:135], v[74:77]
	s_waitcnt lgkmcnt(4)
	v_mfma_f32_16x16x32_bf16 v[78:81], v[136:139], v[128:131], v[78:81]
	s_waitcnt lgkmcnt(3)
	v_mfma_f32_16x16x32_bf16 v[74:77], v[136:139], v[140:143], v[74:77]
	s_waitcnt lgkmcnt(1)
	v_mfma_f32_16x16x32_bf16 v[78:81], v[150:153], v[154:157], v[78:81]
	s_waitcnt lgkmcnt(0)
	v_mfma_f32_16x16x32_bf16 v[74:77], v[150:153], v[158:161], v[74:77]
	s_cbranch_vccnz .LBB0_476
	v_ashrrev_i32_e32 v82, 1, v84
	v_ashrrev_i32_e32 v83, 31, v82
	v_lshlrev_b64 v[82:83], 12, v[82:83]
	v_lshl_add_u64 v[82:83], s[12:13], 0, v[82:83]
	s_mov_b64 s[16:17], 0
